# grid barrier: XCD leaders invalidate first and fire their bookkeeping atomics (generation / release words) without waiting for them, so they enter the next phase with everyone else
# speedup vs baseline: 1.0177x; 1.0063x over previous
.LBB0_253:
	s_or_b64 exec, exec, s[14:15]
	global_atomic_add v1, v236, s[62:63]

.LBB0_519:
	s_or_b64 exec, exec, s[16:17]
	buffer_inv sc1
	s_waitcnt vmcnt(0)
	s_and_saveexec_b64 s[16:17], s[18:19]
	s_cbranch_execz .LBB0_521
	global_atomic_add v[2:3], v236, off
.LBB0_521:
	s_or_b64 exec, exec, s[16:17]
	global_atomic_add v1, v236, s[62:63]

.LBB0_870:
	s_or_b64 exec, exec, s[14:15]
	buffer_inv sc1
	s_waitcnt vmcnt(0)
	s_and_saveexec_b64 s[14:15], s[16:17]
	s_cbranch_execz .LBB0_253
	global_atomic_add v[2:3], v236, off
	s_branch .LBB0_253
